# K-norm (KPART) loop: second load group hoisted above the first wait (renamed registers), on top of the SwiGLU epilogue rewrite
# baseline (speedup 1.0000x reference)
; __device__ __forceinline__ void fox_cumsum_phase(const float* GATE, const float* bfv, float* CUM, const bf16* QKV, float* KPART, LAS unsigned char* lds) {
;     ...
;         for (int i = 0; i < 4; ++i) {
;             const bf16* kp = QKV + ((size_t)b * SEQ + qtr * 2048 + i * 512 + tid) * N_FOX_MAIN + 2048 + h * 64;
;             float ss = 0.f;
; #pragma unroll
;             for (int c = 0; c < 8; ++c) { const v4u w = *(const v4u*)(kp + c * 8); const unsigned ww[4] = {w.x, w.y, w.z, w.w};
; #pragma unroll
;                 for (int e = 0; e < 4; ++e) { const float x0 = bf2f((unsigned short)(ww[e] & 0xffffu)), x1 = bf2f((unsigned short)(ww[e] >> 16)); ss += x0 * x0 + x1 * x1; } }
;             mx = fmaxf(mx, ss);
;         }
; #pragma unroll
;         for (int o = 1; o < 64; o <<= 1) mx = fmaxf(mx, __shfl_xor(mx, o));
;         __syncthreads();
;         if (lane == 0) wmax[wave] = mx;
;         __syncthreads();
;         if (tid == 0) { float t = wmax[0]; for (int w = 1; w < NWAVES; ++w) t = fmaxf(t, wmax[w]); KPART[u] = sqrtf(t); }
.LBB0_286:
	v_lshl_add_u64 v[32:33], v[4:5], 0, s[14:15]
	global_load_dwordx4 v[16:19], v[32:33], off offset:-16
	global_load_dwordx4 v[20:23], v[32:33], off offset:-32
	global_load_dwordx4 v[24:27], v[32:33], off offset:-48
	global_load_dwordx4 v[28:31], v[32:33], off offset:-64
	s_add_u32 s14, s14, 0x600000
	v_max_f32_e32 v14, v14, v14
	s_addc_u32 s15, s15, 0
	s_cmp_lg_u32 s14, 0x1800000
	global_load_dwordx4 v[64:67], v[32:33], off offset:48
	global_load_dwordx4 v[68:71], v[32:33], off offset:32
	global_load_dwordx4 v[72:75], v[32:33], off offset:16
	global_load_dwordx4 v[76:79], v[32:33], off
	s_waitcnt vmcnt(4)
	v_lshlrev_b32_e32 v15, 16, v28
	v_and_b32_e32 v28, 0xffff0000, v28
	v_mul_f32_e32 v28, v28, v28
	v_fmac_f32_e32 v28, v15, v15
	v_lshlrev_b32_e32 v15, 16, v29
	v_and_b32_e32 v29, 0xffff0000, v29
	v_mul_f32_e32 v29, v29, v29
	v_fmac_f32_e32 v29, v15, v15
	v_add_f32_e32 v15, v28, v29
	v_and_b32_e32 v29, 0xffff0000, v30
	v_lshlrev_b32_e32 v28, 16, v30
	v_mul_f32_e32 v29, v29, v29
	v_fmac_f32_e32 v29, v28, v28
	v_add_f32_e32 v15, v29, v15
	v_and_b32_e32 v29, 0xffff0000, v31
	v_lshlrev_b32_e32 v28, 16, v31
	v_mul_f32_e32 v29, v29, v29
	v_fmac_f32_e32 v29, v28, v28
	v_lshlrev_b32_e32 v28, 16, v24
	v_and_b32_e32 v24, 0xffff0000, v24
	v_mul_f32_e32 v24, v24, v24
	v_add_f32_e32 v15, v29, v15
	v_fmac_f32_e32 v24, v28, v28
	v_add_f32_e32 v15, v24, v15
	v_lshlrev_b32_e32 v24, 16, v25
	v_and_b32_e32 v25, 0xffff0000, v25
	v_mul_f32_e32 v25, v25, v25
	v_fmac_f32_e32 v25, v24, v24
	v_add_f32_e32 v15, v25, v15
	v_and_b32_e32 v25, 0xffff0000, v26
	v_lshlrev_b32_e32 v24, 16, v26
	v_mul_f32_e32 v25, v25, v25
	v_fmac_f32_e32 v25, v24, v24
	v_add_f32_e32 v15, v25, v15
	v_and_b32_e32 v25, 0xffff0000, v27
	v_lshlrev_b32_e32 v24, 16, v27
	v_mul_f32_e32 v25, v25, v25
	v_fmac_f32_e32 v25, v24, v24
	v_lshlrev_b32_e32 v24, 16, v20
	v_and_b32_e32 v20, 0xffff0000, v20
	v_mul_f32_e32 v20, v20, v20
	v_add_f32_e32 v15, v25, v15
	v_fmac_f32_e32 v20, v24, v24
	v_add_f32_e32 v15, v20, v15
	v_lshlrev_b32_e32 v20, 16, v21
	v_and_b32_e32 v21, 0xffff0000, v21
	v_mul_f32_e32 v21, v21, v21
	v_fmac_f32_e32 v21, v20, v20
	v_add_f32_e32 v15, v21, v15
	v_and_b32_e32 v21, 0xffff0000, v22
	v_lshlrev_b32_e32 v20, 16, v22
	v_mul_f32_e32 v21, v21, v21
	v_fmac_f32_e32 v21, v20, v20
	v_add_f32_e32 v15, v21, v15
	v_and_b32_e32 v21, 0xffff0000, v23
	v_lshlrev_b32_e32 v20, 16, v23
	v_mul_f32_e32 v21, v21, v21
	v_fmac_f32_e32 v21, v20, v20
	v_lshlrev_b32_e32 v20, 16, v16
	v_and_b32_e32 v16, 0xffff0000, v16
	v_mul_f32_e32 v16, v16, v16
	v_add_f32_e32 v15, v21, v15
	v_fmac_f32_e32 v16, v20, v20
	v_add_f32_e32 v15, v16, v15
	v_lshlrev_b32_e32 v16, 16, v17
	v_and_b32_e32 v17, 0xffff0000, v17
	v_mul_f32_e32 v17, v17, v17
	v_fmac_f32_e32 v17, v16, v16
	v_add_f32_e32 v15, v17, v15
	v_and_b32_e32 v17, 0xffff0000, v18
	v_lshlrev_b32_e32 v16, 16, v18
	v_mul_f32_e32 v17, v17, v17
	v_fmac_f32_e32 v17, v16, v16
	v_add_f32_e32 v15, v17, v15
	v_and_b32_e32 v17, 0xffff0000, v19
	v_lshlrev_b32_e32 v16, 16, v19
	v_mul_f32_e32 v17, v17, v17
	v_fmac_f32_e32 v17, v16, v16
	v_add_f32_e32 v15, v17, v15
	s_waitcnt vmcnt(0)
	v_lshlrev_b32_e32 v32, 16, v76
	v_and_b32_e32 v76, 0xffff0000, v76
	v_mul_f32_e32 v76, v76, v76
	v_fmac_f32_e32 v76, v32, v32
	v_add_f32_e32 v15, v76, v15
	v_lshlrev_b32_e32 v76, 16, v77
	v_and_b32_e32 v77, 0xffff0000, v77
	v_mul_f32_e32 v77, v77, v77
	v_fmac_f32_e32 v77, v76, v76
	v_add_f32_e32 v15, v77, v15
	v_and_b32_e32 v77, 0xffff0000, v78
	v_lshlrev_b32_e32 v76, 16, v78
	v_mul_f32_e32 v77, v77, v77
	v_fmac_f32_e32 v77, v76, v76
	v_add_f32_e32 v15, v77, v15
	v_and_b32_e32 v77, 0xffff0000, v79
	v_lshlrev_b32_e32 v76, 16, v79
	v_mul_f32_e32 v77, v77, v77
	v_fmac_f32_e32 v77, v76, v76
	v_add_f32_e32 v15, v77, v15
	v_lshlrev_b32_e32 v77, 16, v73
	v_lshlrev_b32_e32 v76, 16, v72
	v_and_b32_e32 v73, 0xffff0000, v73
	v_and_b32_e32 v72, 0xffff0000, v72
	v_pk_mul_f32 v[72:73], v[72:73], v[72:73]
	s_nop 0
	v_pk_fma_f32 v[72:73], v[76:77], v[76:77], v[72:73]
	s_nop 0
	v_add_f32_e32 v15, v72, v15
	v_add_f32_e32 v15, v73, v15
	v_lshlrev_b32_e32 v73, 16, v75
	v_lshlrev_b32_e32 v72, 16, v74
	v_and_b32_e32 v75, 0xffff0000, v75
	v_and_b32_e32 v74, 0xffff0000, v74
	v_pk_mul_f32 v[74:75], v[74:75], v[74:75]
	s_nop 0
	v_pk_fma_f32 v[72:73], v[72:73], v[72:73], v[74:75]
	s_nop 0
	v_add_f32_e32 v15, v72, v15
	v_add_f32_e32 v15, v73, v15
	v_lshlrev_b32_e32 v73, 16, v69
	v_lshlrev_b32_e32 v72, 16, v68
	v_and_b32_e32 v69, 0xffff0000, v69
	v_and_b32_e32 v68, 0xffff0000, v68
	v_pk_mul_f32 v[68:69], v[68:69], v[68:69]
	s_nop 0
	v_pk_fma_f32 v[68:69], v[72:73], v[72:73], v[68:69]
	s_nop 0
	v_add_f32_e32 v15, v68, v15
	v_add_f32_e32 v15, v69, v15
	v_lshlrev_b32_e32 v69, 16, v71
	v_lshlrev_b32_e32 v68, 16, v70
	v_and_b32_e32 v71, 0xffff0000, v71
	v_and_b32_e32 v70, 0xffff0000, v70
	v_pk_mul_f32 v[70:71], v[70:71], v[70:71]
	s_nop 0
	v_pk_fma_f32 v[68:69], v[68:69], v[68:69], v[70:71]
	s_nop 0
	v_add_f32_e32 v15, v68, v15
	v_add_f32_e32 v15, v69, v15
	v_lshlrev_b32_e32 v69, 16, v65
	v_lshlrev_b32_e32 v68, 16, v64
	v_and_b32_e32 v65, 0xffff0000, v65
	v_and_b32_e32 v64, 0xffff0000, v64
	v_pk_mul_f32 v[64:65], v[64:65], v[64:65]
	s_nop 0
	v_pk_fma_f32 v[64:65], v[68:69], v[68:69], v[64:65]
	s_nop 0
	v_add_f32_e32 v15, v64, v15
	v_add_f32_e32 v15, v65, v15
	v_lshlrev_b32_e32 v65, 16, v67
	v_lshlrev_b32_e32 v64, 16, v66
	v_and_b32_e32 v67, 0xffff0000, v67
	v_and_b32_e32 v66, 0xffff0000, v66
	v_pk_mul_f32 v[66:67], v[66:67], v[66:67]
	s_nop 0
	v_pk_fma_f32 v[64:65], v[64:65], v[64:65], v[66:67]
	s_nop 0
	v_add_f32_e32 v15, v64, v15
	v_add_f32_e32 v15, v65, v15
	v_max_f32_e32 v14, v14, v15
	s_cbranch_scc1 .LBB0_286
	ds_bpermute_b32 v4, v8, v14
	v_max_f32_e32 v5, v14, v14
	s_waitcnt lgkmcnt(0)
	s_barrier
	v_max_f32_e32 v4, v4, v4
	v_max_f32_e32 v4, v5, v4
	ds_bpermute_b32 v5, v9, v4
	s_waitcnt lgkmcnt(0)
	v_max_f32_e32 v5, v5, v5
	v_max_f32_e32 v4, v4, v5
	ds_bpermute_b32 v5, v10, v4
	s_waitcnt lgkmcnt(0)
	v_max_f32_e32 v5, v5, v5
	v_max_f32_e32 v4, v4, v5
	ds_bpermute_b32 v5, v11, v4
	s_waitcnt lgkmcnt(0)
	v_max_f32_e32 v5, v5, v5
	v_max_f32_e32 v4, v4, v5
	ds_bpermute_b32 v5, v12, v4
	s_waitcnt lgkmcnt(0)
	v_max_f32_e32 v5, v5, v5
	v_max_f32_e32 v4, v4, v5
	ds_bpermute_b32 v5, v13, v4
	s_and_saveexec_b64 s[14:15], s[40:41]
	s_cbranch_execz .LBB0_289
	s_waitcnt lgkmcnt(0)
	v_max_f32_e32 v5, v5, v5
	v_max_f32_e32 v4, v4, v4
	v_max_f32_e32 v4, v4, v5
	ds_write_b32 v7, v4 offset:256
